# one static s_setprio 1 for waves 4-7 across the attention item loop (reset to 0 after it)
# baseline (speedup 1.0000x reference)
; DI void phase_attn(const Params& p, int l, bool last, char* smem) {
;     ...
;     float* red = (float*)smem;
;     if ((tid & 63) == 0) { const int w = tid >> 6; red[w * 8 + 0] = a; red[w * 8 + 1] = b2; red[w * 8 + 2] = c; red[w * 8 + 3] = d; red[w * 8 + 4] = e; }
;     __syncthreads();
;     a = b2 = c = d = e = 0.f;
; #pragma unroll
;     for (int w = 0; w < 8; ++w) { a = fmaxf(a, red[w * 8]); b2 = fmaxf(b2, red[w * 8 + 1]); c = fmaxf(c, red[w * 8 + 2]); d = fmaxf(d, red[w * 8 + 3]); e = fmaxf(e, red[w * 8 + 4]); }
;     __syncthreads();
;     m0_mla = c_mla * 96.f * a * b2;
;     m0_na = c_na * 64.f * c * d + e * LOG2E;
;   }
;   const bool smax_mla = m0_mla < 64.f, smax_na = m0_na < 64.f;
;   for (int item = blockIdx.x; item < 1024; item += gridDim.x) {
.LBB0_990:
	s_or_b64 exec, exec, s[0:1]
	s_waitcnt lgkmcnt(0)
	s_barrier
	ds_read2_b32 v[40:41], v1 offset0:4 offset1:12
	ds_read_b128 v[22:25], v1
	ds_read_b128 v[30:33], v1 offset:32
	ds_read2_b32 v[38:39], v1 offset0:20 offset1:28
	ds_read_b128 v[14:17], v1 offset:64
	ds_read_b128 v[26:29], v1 offset:96
	ds_read2_b32 v[36:37], v1 offset0:36 offset1:44
	ds_read_b128 v[6:9], v1 offset:128
	ds_read_b128 v[18:21], v1 offset:160
	ds_read2_b32 v[34:35], v1 offset0:52 offset1:60
	ds_read_b128 v[2:5], v1 offset:192
	ds_read_b128 v[10:13], v1 offset:224
	v_readlane_b32 s0, v251, 13
	v_readlane_b32 s1, v251, 14
	s_andn2_b64 vcc, exec, s[0:1]
	s_waitcnt lgkmcnt(0)
	v_cndmask_b32_e64 v0, 0, 1, s[0:1]
	v_cmp_ne_u32_e64 s[4:5], 1, v0
	s_barrier
	s_nop 0
	v_writelane_b32 v248, s4, 14
	s_nop 1
	v_writelane_b32 v248, s5, 15
	s_cbranch_vccnz .LBB0_1149
	v_max3_f32 v0, v22, 0, v30
	v_max3_f32 v22, v23, 0, v31
	v_max3_f32 v23, v24, 0, v32
	v_max3_f32 v24, v25, 0, v33
	v_max3_f32 v25, v40, 0, v41
	v_max3_f32 v0, v0, v14, v26
	v_max3_f32 v14, v22, v15, v27
	v_max3_f32 v15, v23, v16, v28
	v_max3_f32 v16, v24, v17, v29
	v_max3_f32 v17, v25, v38, v39
	v_max3_f32 v0, v0, v6, v18
	v_max3_f32 v6, v14, v7, v19
	v_max3_f32 v7, v15, v8, v20
	v_max3_f32 v8, v16, v9, v21
	v_max3_f32 v9, v17, v36, v37
	s_mov_b32 s0, 0x4138aa3b
	v_max3_f32 v0, v0, v2, v10
	v_max3_f32 v6, v6, v3, v11
	v_max3_f32 v2, v7, v4, v12
	v_max3_f32 v3, v9, v34, v35
	s_mov_b32 s1, 0x3fb8aa3b
	v_max3_f32 v4, v8, v5, v13
	v_mul_f32_e32 v0, 0x41622ae0, v0
	v_pk_mul_f32 v[152:153], v[2:3], s[0:1]
	v_mul_f32_e32 v188, v6, v0
	v_fmac_f32_e32 v153, v4, v152
	s_mov_b32 s0, 0x42800000
	v_cmp_ngt_f32_e64 s[58:59], s0, v188
	v_cmp_ngt_f32_e64 s[60:61], s0, v153
	v_readlane_b32 s0, v248, 4
	v_readlane_b32 s1, v248, 5
	v_writelane_b32 v248, s58, 16
	s_lshl_b32 s55, s0, 3
	s_mov_b32 s30, s97
	v_writelane_b32 v248, s59, 17
	v_writelane_b32 v248, s60, 18
	s_mov_b32 s18, s97
	s_nop 0
	v_writelane_b32 v248, s61, 19
	v_writelane_b32 v248, s55, 20
	v_readfirstlane_b32 s100, v149
	s_nop 3
	s_cmpk_ge_u32 s100, 0x100
	s_cbranch_scc0 .Lprio_skip
	s_setprio 1
.Lprio_skip:
	s_branch .LBB0_994

; DI int otid() { int t = threadIdx.x; asm volatile("" : "+v"(t)); return t; }
; #define STG_A(P, ptr) do { const bf16_t* _g = (ptr); \
;     __builtin_amdgcn_global_load_lds((const unsigned*)(_g + oa0), (__attribute__((address_space(3))) unsigned*)((P) + tb0), 16, 0, 0); \
;     __builtin_amdgcn_global_load_lds((const unsigned*)(_g + (size_t)64 * lda + oa0), (__attribute__((address_space(3))) unsigned*)((P) + tb1), 16, 0, 0); } while (0)
; #define STG_B(P, ptr) do { const bf16_t* _g = (ptr); \
;     __builtin_amdgcn_global_load_lds((const unsigned*)(_g + ob0), (__attribute__((address_space(3))) unsigned*)((P) + tb0), 16, 0, 0); \
;     __builtin_amdgcn_global_load_lds((const unsigned*)(_g + (size_t)64 * ldb + ob0), (__attribute__((address_space(3))) unsigned*)((P) + tb1), 16, 0, 0); } while (0)
; #define BAR __builtin_amdgcn_s_barrier()
; template <int lda, int ldb, int K, class Gen, class Epi>
; DI void gemm_stream(Gen gen, Epi epi) {
;     ...
;   const bf16_t *A, *Bt;
;   if (!gen(0, A, Bt)) return;
;   const int tid = otid(), wid = tid >> 6, lane = tid & 63, wr = wid >> 2, wc = wid & 3, fr = lane & 15, fq = lane >> 4;
;   const int tb0 = tid * 16, tb1 = tid * 16 + 8192;
;   int r0_, c0_;
;   stage_rc(tb0, r0_, c0_);
;   const int r0p = (r0_ & ~31) | perm32(r0_ & 31);
;   const unsigned oa0 = (unsigned)(r0_ * lda + c0_), ob0 = (unsigned)(r0p * ldb + c0_);
;   acc_t acc;
;   bf16x8 At[4][2], B0[2][2], B1[2][2];
;   STG_B(SB(0, 0), Bt); STG_A(SA(0, 0), A);
;   STG_B(SB(0, 1), Bt + (size_t)128 * ldb); STG_A(SA(0, 1), A + (size_t)128 * lda);
;   if (wr == 1) BAR;
.LBB0_1149:
	s_setprio 0
	v_readlane_b32 s4, v249, 0
	v_readlane_b32 s5, v249, 1
	s_load_dword s0, s[4:5], 0x10
	s_nop 0
	s_load_dword s4, s[4:5], 0x0
	v_readlane_b32 s1, v248, 11
	s_add_u32 s1, s20, s1
	s_nop 0
	v_writelane_b32 v248, s1, 21
	s_addc_u32 s1, s21, 0
	s_waitcnt lgkmcnt(0)
	s_lshr_b32 s0, s0, 16
	s_cmp_lg_u32 s0, 0
	v_writelane_b32 v248, s1, 23
	s_cselect_b64 s[0:1], -1, 0
	s_cmp_lg_u64 s[0:1], 0
	v_readlane_b32 s0, v251, 15
	v_readlane_b32 s1, v251, 16
	s_addc_u32 s18, s4, 0
	s_andn2_b64 vcc, exec, s[0:1]
	s_cbranch_vccnz .LBB0_1163
	v_mov_b32_e32 v136, v149
	v_readlane_b32 s0, v253, 13
	v_ashrrev_i32_e32 v2, 31, v136
	v_lshrrev_b32_e32 v2, 26, v2
	v_add_u32_e32 v2, v136, v2
	v_ashrrev_i32_e32 v6, 6, v2
	v_bfe_i32 v2, v136, 27, 1
	v_lshlrev_b32_e32 v10, 4, v136
	v_lshrrev_b32_e32 v2, 22, v2
	v_add_u32_e32 v2, v10, v2
	v_and_b32_e32 v2, 0xfffffc00, v2
	v_sub_u32_e32 v2, v10, v2
	v_lshrrev_b32_e32 v3, 4, v2
	v_bitop3_b32 v3, v3, v2, 32 bitop3:0x6c
	v_ashrrev_i32_e32 v2, 31, v2
	v_lshrrev_b32_e32 v2, 26, v2
	v_lshlrev_b32_e32 v4, 3, v6
	v_add_u32_e32 v2, v3, v2
	v_and_b32_e32 v4, -16, v4
	v_ashrrev_i32_e32 v7, 6, v2
	v_readlane_b32 s4, v248, 21
	v_add_u32_e32 v2, v7, v4
	v_lshlrev_b32_e32 v4, 5, v6
	v_readlane_b32 s1, v253, 14
	s_add_u32 s42, s4, s0
	v_readlane_b32 s0, v248, 23
	v_and_b32_e32 v8, 32, v4
	v_mul_i32_i24_e32 v4, 64, v7
	s_addc_u32 s43, s0, s1
	v_sub_u32_e32 v3, v3, v4
	v_lshlrev_b32_e32 v4, 1, v2
	v_lshrrev_b32_e32 v5, 2, v2
	v_and_b32_e32 v12, 3, v7
	s_mov_b32 s0, 0x3fffe0
	v_ashrrev_i16_sdwa v9, v191, sext(v3) dst_sel:DWORD dst_unused:UNUSED_PAD src0_sel:DWORD src1_sel:BYTE_0
	v_and_b32_e32 v4, 24, v4
	v_and_b32_e32 v5, 4, v5
	v_and_or_b32 v12, v2, s0, v12
	v_readlane_b32 s1, v254, 26
	v_add_u32_e32 v11, 0x2000, v10
	v_add_u32_sdwa v3, v8, sext(v9) dst_sel:DWORD dst_unused:UNUSED_PAD src0_sel:DWORD src1_sel:WORD_0
	v_or3_b32 v4, v12, v5, v4
	v_add_u32_e32 v137, s1, v10
	v_lshl_add_u32 v132, v4, 10, v3
	v_mov_b32_e32 v133, v1
	v_readfirstlane_b32 s0, v137
	v_add_u32_e32 v12, s1, v11
	v_lshl_add_u32 v130, v2, 10, v3
	v_lshl_add_u64 v[2:3], v[132:133], 1, s[42:43]
	s_mov_b32 m0, s0
	v_readfirstlane_b32 s0, v12
	global_load_lds_dwordx4 v[2:3], off
	s_mov_b32 m0, s0
	v_mov_b32_e32 v131, v1
	v_readlane_b32 s0, v251, 24
	v_lshl_add_u64 v[4:5], v[2:3], 0, s[24:25]
	v_lshlrev_b64 v[12:13], 1, v[130:131]
	v_readlane_b32 s1, v251, 25
	v_add_u32_e32 v138, 0, v10
	global_load_lds_dwordx4 v[4:5], off
	v_lshl_add_u64 v[4:5], s[0:1], 0, v[12:13]
	v_readfirstlane_b32 s0, v138
	s_mov_b32 m0, s0
	v_readlane_b32 s0, v251, 18
	v_readlane_b32 s1, v251, 19
	v_add_u32_e32 v139, 0x2000, v138
	global_load_lds_dwordx4 v[4:5], off
	v_lshl_add_u64 v[14:15], s[0:1], 0, v[12:13]
	v_readlane_b32 s1, v254, 27
	v_readfirstlane_b32 s0, v139
	s_mov_b32 m0, s0
	v_add_u32_e32 v140, s1, v10
	v_add_u32_e32 v11, s1, v11
	v_readfirstlane_b32 s0, v140
	global_load_lds_dwordx4 v[14:15], off
	v_lshl_add_u64 v[14:15], v[2:3], 0, s[38:39]
	s_mov_b32 m0, s0
	v_readfirstlane_b32 s0, v11
	global_load_lds_dwordx4 v[14:15], off
	s_mov_b32 m0, s0
	v_readlane_b32 s0, v251, 20
	v_lshl_add_u64 v[14:15], v[2:3], 0, s[12:13]
	v_readlane_b32 s1, v251, 21
	v_add_u32_e32 v141, 0x4000, v138
	global_load_lds_dwordx4 v[14:15], off
	v_lshl_add_u64 v[14:15], s[0:1], 0, v[12:13]
	v_readfirstlane_b32 s0, v141
	s_mov_b32 m0, s0
	v_readlane_b32 s0, v251, 22
	v_readlane_b32 s1, v251, 23
	v_add_u32_e32 v142, 0x6000, v138
	global_load_lds_dwordx4 v[14:15], off
	v_lshl_add_u64 v[12:13], s[0:1], 0, v[12:13]
	v_readfirstlane_b32 s0, v142
	s_mov_b32 m0, s0
	v_ashrrev_i32_e32 v0, 8, v136
	global_load_lds_dwordx4 v[12:13], off
	v_cmp_eq_u32_e32 vcc, 1, v0
	s_and_saveexec_b64 s[0:1], vcc
	s_cbranch_execz .LBB0_1152
	s_barrier
